# adds: window-branch bias reads issued up front; conv-1 bias partial sums loaded together (im2col phase)
# speedup vs baseline: 1.0407x; 1.0038x over previous
.LBB0_131:
	s_or_b64 exec, exec, s[4:5]
	v_readlane_b32 s0, v246, 20
	v_readlane_b32 s1, v246, 21
	s_and_b64 vcc, exec, s[0:1]
	s_cbranch_vccz .LBB0_135
	v_and_b32_e32 v0, 0xff, v150
	s_movk_i32 s0, 0x80
	v_cmp_gt_u32_e32 vcc, s0, v0
	v_mov_b32_e32 v1, 0
	s_and_saveexec_b64 s[0:1], vcc
	s_cbranch_execz .LBB0_134
	v_readlane_b32 s2, v244, 34
	v_ashrrev_i32_e32 v1, 8, v150
	v_lshl_or_b32 v6, v1, 7, v0
	v_mov_b32_e32 v2, s2
	ds_read_b128 v[2:5], v2 offset:64
	v_lshl_or_b32 v0, v1, 12, v0
	v_ashrrev_i32_e32 v7, 31, v6
	v_ashrrev_i32_e32 v1, 31, v0
	s_movk_i32 s2, 0x1000
	s_waitcnt lgkmcnt(0)
	v_lshl_add_u64 v[4:5], v[6:7], 2, v[4:5]
	v_lshl_add_u64 v[0:1], v[0:1], 2, v[2:3]
	flat_load_dword v4, v[4:5]
	v_add_co_u32_e32 v42, vcc, 0x1000, v0
	s_nop 1
	v_addc_co_u32_e32 v43, vcc, 0, v1, vcc
	v_add_co_u32_e32 v44, vcc, 0x2000, v0
	s_nop 1
	v_addc_co_u32_e32 v45, vcc, 0, v1, vcc
	v_add_co_u32_e32 v46, vcc, 0x3000, v0
	s_nop 1
	v_addc_co_u32_e32 v47, vcc, 0, v1, vcc
	flat_load_dword v8, v[0:1]
	flat_load_dword v9, v[0:1] offset:512
	flat_load_dword v10, v[0:1] offset:1024
	flat_load_dword v11, v[0:1] offset:1536
	flat_load_dword v12, v[0:1] offset:2048
	flat_load_dword v13, v[0:1] offset:2560
	flat_load_dword v14, v[0:1] offset:3072
	flat_load_dword v15, v[0:1] offset:3584
	flat_load_dword v16, v[42:43]
	flat_load_dword v17, v[42:43] offset:512
	flat_load_dword v18, v[42:43] offset:1024
	flat_load_dword v19, v[42:43] offset:1536
	flat_load_dword v20, v[42:43] offset:2048
	flat_load_dword v21, v[42:43] offset:2560
	flat_load_dword v22, v[42:43] offset:3072
	flat_load_dword v23, v[42:43] offset:3584
	flat_load_dword v24, v[44:45]
	flat_load_dword v25, v[44:45] offset:512
	flat_load_dword v26, v[44:45] offset:1024
	flat_load_dword v27, v[44:45] offset:1536
	flat_load_dword v30, v[44:45] offset:2048
	flat_load_dword v31, v[44:45] offset:2560
	flat_load_dword v32, v[44:45] offset:3072
	flat_load_dword v33, v[44:45] offset:3584
	flat_load_dword v34, v[46:47]
	flat_load_dword v35, v[46:47] offset:512
	flat_load_dword v36, v[46:47] offset:1024
	flat_load_dword v37, v[46:47] offset:1536
	flat_load_dword v38, v[46:47] offset:2048
	flat_load_dword v39, v[46:47] offset:2560
	flat_load_dword v40, v[46:47] offset:3072
	flat_load_dword v41, v[46:47] offset:3584
	s_waitcnt vmcnt(0) lgkmcnt(0)
	v_add_f32_e32 v2, v4, v8
	v_add_f32_e32 v2, v2, v9
	v_add_f32_e32 v2, v2, v10
	v_add_f32_e32 v2, v2, v11
	v_add_f32_e32 v2, v2, v12
	v_add_f32_e32 v2, v2, v13
	v_add_f32_e32 v2, v2, v14
	v_add_f32_e32 v2, v2, v15
	v_add_f32_e32 v2, v2, v16
	v_add_f32_e32 v2, v2, v17
	v_add_f32_e32 v2, v2, v18
	v_add_f32_e32 v2, v2, v19
	v_add_f32_e32 v2, v2, v20
	v_add_f32_e32 v2, v2, v21
	v_add_f32_e32 v2, v2, v22
	v_add_f32_e32 v2, v2, v23
	v_add_f32_e32 v2, v2, v24
	v_add_f32_e32 v2, v2, v25
	v_add_f32_e32 v2, v2, v26
	v_add_f32_e32 v2, v2, v27
	v_add_f32_e32 v2, v2, v30
	v_add_f32_e32 v2, v2, v31
	v_add_f32_e32 v2, v2, v32
	v_add_f32_e32 v2, v2, v33
	v_add_f32_e32 v2, v2, v34
	v_add_f32_e32 v2, v2, v35
	v_add_f32_e32 v2, v2, v36
	v_add_f32_e32 v2, v2, v37
	v_add_f32_e32 v2, v2, v38
	v_add_f32_e32 v2, v2, v39
	v_add_f32_e32 v2, v2, v40
	v_add_f32_e32 v1, v2, v41
